# one static s_setprio 1 for the later-dispatched co-resident blocks (256..511) at the start of P3 (attention) and P8
# baseline (speedup 1.0000x reference)
.LBB0_917:
	s_or_b64 exec, exec, s[6:7]
	v_lshrrev_b32_e32 v3, 6, v204
	v_lshl_add_u32 v4, s2, 2, v3
	s_cmp_ge_u32 s2, 0x100
	s_cbranch_scc0 .Lprio8_skip
	s_setprio 1
.Lprio8_skip:
	s_mov_b32 s89, s2
	s_load_dword s88, s[0:1], 0x120
	s_waitcnt lgkmcnt(0)
	s_cmp_eq_u32 s88, 0x200
	s_mov_b32 s87, 0x2200
	s_cselect_b32 s87, 0x2000, s87
	s_cselect_b32 s85, 1, 0
	s_mov_b32 s2, s87
	s_sub_u32 s87, s87, 1
	v_cmp_gt_i32_e32 vcc, s2, v4
	s_and_saveexec_b64 s[2:3], vcc
	s_cbranch_execz .LBB0_930
	v_and_b32_e32 v6, 32, v204
	s_add_u32 s74, s94, 0x1cb18000
	v_cmp_eq_u32_e64 s[8:9], 0, v6
	v_lshlrev_b32_e32 v6, 5, v0
	v_mov_b32_e32 v7, 0
	s_addc_u32 s75, s95, 0
	v_lshl_add_u64 v[8:9], s[94:95], 0, v[6:7]
	s_mov_b64 s[10:11], 0x13288000
	v_and_b32_e32 v6, 2, v204
	v_and_b32_e32 v10, 1, v204
	s_add_u32 s76, s94, 0x1cb08000
	v_lshl_add_u64 v[8:9], v[8:9], 0, s[10:11]
	v_cmp_ne_u32_e32 vcc, 0, v6
	v_cmp_eq_u32_e64 s[10:11], 0, v10
	v_and_b32_e32 v10, 4, v204
	s_addc_u32 s77, s95, 0
	s_xor_b64 s[12:13], vcc, s[10:11]
	v_cmp_ne_u32_e32 vcc, 0, v10
	v_cmp_eq_u32_e64 s[14:15], 0, v6
	v_and_b32_e32 v6, 8, v204
	v_lshlrev_b32_e32 v5, 10, v3
	v_and_b32_e32 v3, 16, v204
	s_xor_b64 s[16:17], vcc, s[14:15]
	s_xor_b64 s[18:19], vcc, s[10:11]
	v_cmp_ne_u32_e32 vcc, 0, v6
	v_cmp_eq_u32_e64 s[20:21], 0, v10
	v_cmp_eq_u32_e64 s[6:7], 0, v3
	s_xor_b64 s[22:23], vcc, s[20:21]
	s_xor_b64 s[24:25], vcc, s[14:15]
	s_xor_b64 s[26:27], vcc, s[10:11]
	v_cmp_ne_u32_e32 vcc, 0, v3
	v_mbcnt_lo_u32_b32 v3, -1, 0
	v_mbcnt_hi_u32_b32 v3, -1, v3
	s_load_dword s33, s[0:1], 0x120
	v_and_b32_e32 v166, 64, v3
	v_cndmask_b32_e64 v2, v2, 0, s[4:5]
	v_cmp_eq_u32_e64 s[28:29], 0, v6
	v_or_b32_e32 v2, v166, v2
	v_lshlrev_b32_e32 v6, 3, v0
	v_lshlrev_b32_e32 v167, 2, v2
	v_cndmask_b32_e64 v1, v1, 0, s[4:5]
	v_lshl_add_u64 v[2:3], s[94:95], 0, v[6:7]
	s_mov_b64 s[60:61], 0x8000
	v_lshlrev_b32_e32 v6, 6, v0
	v_cmp_lt_u32_e64 s[40:41], 31, v0
	v_or_b32_e32 v1, v166, v1
	v_lshl_add_u64 v[10:11], v[2:3], 0, s[60:61]
	s_mov_b64 s[60:61], 0x4008000
	v_lshl_add_u64 v[14:15], s[92:93], 0, v[6:7]
	v_lshlrev_b32_e32 v6, 2, v0
	v_add_u32_e32 v169, 32, v5
	s_movk_i32 s78, 0x7f
	v_xor_b32_e32 v164, 0x7f, v0
	v_xor_b32_e32 v165, 63, v0
	s_xor_b64 s[30:31], vcc, s[28:29]
	s_xor_b64 s[34:35], vcc, s[20:21]
	s_xor_b64 s[36:37], vcc, s[14:15]
	s_xor_b64 s[38:39], vcc, s[10:11]
	s_xor_b64 s[42:43], s[40:41], s[6:7]
	s_xor_b64 s[44:45], s[40:41], s[28:29]
	s_xor_b64 s[46:47], s[40:41], s[20:21]
	s_xor_b64 s[48:49], s[40:41], s[14:15]
	s_xor_b64 s[50:51], s[40:41], s[10:11]
	v_cmp_gt_u32_e64 s[52:53], 32, v0
	v_lshlrev_b32_e32 v168, 2, v1
	v_cmp_gt_u32_e64 s[54:55], 16, v0
	v_lshl_add_u64 v[12:13], v[2:3], 0, s[60:61]
	s_waitcnt lgkmcnt(0)
	s_lshl_b32 s79, s33, 2
	v_add_u32_e32 v170, v169, v6
	v_lshl_add_u64 v[16:17], s[94:95], 0, v[6:7]
	v_add_u32_e32 v6, 16, v169
	s_mov_b64 s[60:61], 0
	s_mov_b64 s[62:63], 0x1000
	s_movk_i32 s80, 0x1000
	v_mov_b32_e32 v171, 0x358637bd
	s_mov_b32 s81, 0x800000
	s_mov_b32 s82, 0xc0e00000
	s_mov_b32 s83, 0x3e6d3388
	v_mov_b32_e32 v172, 0xbf3a00e3
	s_mov_b32 s84, s87
	v_bfrev_b32_e32 v173, 1
	v_mov_b32_e32 v174, 0x40e00000
	s_branch .LBB0_920
